# P2 residual epilogue pipelined 4 deep as P8 (saddr + 32-bit row-group offsets, counted vmcnt)
# baseline (speedup 1.0000x reference)
;     __device__ __forceinline__ void operator()(const f32x4 (&acc)[2][2][4][2], const Unit& u, int wr, int wc, int fr, int fq) const {
;         const int row0 = u.pm * BM + wr * 64 + fr; const int col0 = u.pn * BM + wc * 32 + 4 * fq;
; #pragma unroll
;         for (int ai = 0; ai < 2; ++ai)
; #pragma unroll
;             for (int m = 0; m < 4; ++m) { const size_t off = (size_t)(row0 + ai * HALF + m * 16) * D + col0;
; #pragma unroll
;                 for (int bj = 0; bj < 2; ++bj)
; #pragma unroll
;                     for (int n = 0; n < 2; ++n) { const size_t o = off + bj * HALF + n * 16; const f32x4 rv = *(const f32x4*)(res + o); *(f32x4*)(out + o) = rv * alpha + acc[ai][bj][m][n] * s; } }
;     }
.LBB0_167:
	v_lshl_add_u32 v154, s70, 8, v144
	v_lshl_or_b32 v156, s71, 8, v146
	v_ashrrev_i32_e32 v155, 31, v154
	v_ashrrev_i32_e32 v157, 31, v156
	v_lshlrev_b64 v[142:143], 10, v[154:155]
	v_lshl_add_u64 v[142:143], v[142:143], 0, v[156:157]
	v_lshlrev_b64 v[142:143], 2, v[142:143]
	v_lshl_add_u64 v[158:159], s[12:13], 0, v[142:143]
	v_lshl_add_u64 v[160:161], s[84:85], 0, v[142:143]
	s_mov_b64 s[30:31], 0xb0000
	s_and_b64 vcc, exec, s[0:1]
	s_mov_b64 s[0:1], -1
	v_add_u32_e32 v225, 0x10000, v142
	v_add_u32_e32 v226, 0x20000, v142
	v_add_u32_e32 v227, 0x30000, v142
	v_add_u32_e32 v228, 0x80000, v142
	v_add_u32_e32 v229, 0x90000, v142
	v_add_u32_e32 v230, 0xa0000, v142
	v_add_u32_e32 v231, 0xb0000, v142
	global_load_dwordx4 v[240:243], v142, s[12:13]
	global_load_dwordx4 v[244:247], v142, s[12:13] offset:64
	global_load_dwordx4 v[248:251], v142, s[12:13] offset:512
	global_load_dwordx4 v[252:255], v142, s[12:13] offset:576
	s_waitcnt vmcnt(3)
	v_pk_mul_f32 v[242:243], v[242:243], s[10:11] op_sel_hi:[1,0]
	v_pk_mul_f32 v[240:241], v[240:241], s[10:11] op_sel_hi:[1,0]
	v_pk_fma_f32 v[128:129], v[128:129], 0.5, v[242:243] op_sel_hi:[1,0,1]
	v_pk_fma_f32 v[126:127], v[126:127], 0.5, v[240:241] op_sel_hi:[1,0,1]
	global_store_dwordx4 v142, v[126:129], s[84:85]
	global_load_dwordx4 v[240:243], v225, s[12:13]
	s_waitcnt vmcnt(4)
	v_pk_mul_f32 v[246:247], v[246:247], s[10:11] op_sel_hi:[1,0]
	v_pk_mul_f32 v[244:245], v[244:245], s[10:11] op_sel_hi:[1,0]
	v_pk_fma_f32 v[124:125], v[124:125], 0.5, v[246:247] op_sel_hi:[1,0,1]
	v_pk_fma_f32 v[122:123], v[122:123], 0.5, v[244:245] op_sel_hi:[1,0,1]
	global_store_dwordx4 v142, v[122:125], s[84:85] offset:64
	global_load_dwordx4 v[244:247], v225, s[12:13] offset:64
	s_waitcnt vmcnt(5)
	v_pk_mul_f32 v[250:251], v[250:251], s[10:11] op_sel_hi:[1,0]
	v_pk_mul_f32 v[248:249], v[248:249], s[10:11] op_sel_hi:[1,0]
	v_pk_fma_f32 v[120:121], v[120:121], 0.5, v[250:251] op_sel_hi:[1,0,1]
	v_pk_fma_f32 v[118:119], v[118:119], 0.5, v[248:249] op_sel_hi:[1,0,1]
	global_store_dwordx4 v142, v[118:121], s[84:85] offset:512
	global_load_dwordx4 v[248:251], v225, s[12:13] offset:512
	s_waitcnt vmcnt(6)
	v_pk_mul_f32 v[254:255], v[254:255], s[10:11] op_sel_hi:[1,0]
	v_pk_mul_f32 v[252:253], v[252:253], s[10:11] op_sel_hi:[1,0]
	v_pk_fma_f32 v[112:113], v[112:113], 0.5, v[254:255] op_sel_hi:[1,0,1]
	v_pk_fma_f32 v[110:111], v[110:111], 0.5, v[252:253] op_sel_hi:[1,0,1]
	global_store_dwordx4 v142, v[110:113], s[84:85] offset:576
	global_load_dwordx4 v[252:255], v225, s[12:13] offset:576
	s_waitcnt vmcnt(6)
	v_pk_mul_f32 v[242:243], v[242:243], s[10:11] op_sel_hi:[1,0]
	v_pk_mul_f32 v[240:241], v[240:241], s[10:11] op_sel_hi:[1,0]
	s_nop 1
	v_pk_fma_f32 v[112:113], v[116:117], 0.5, v[242:243] op_sel_hi:[1,0,1]
	s_nop 1
	v_pk_fma_f32 v[110:111], v[114:115], 0.5, v[240:241] op_sel_hi:[1,0,1]
	global_store_dwordx4 v225, v[110:113], s[84:85]
	global_load_dwordx4 v[240:243], v226, s[12:13]
	s_waitcnt vmcnt(6)
	v_pk_mul_f32 v[246:247], v[246:247], s[10:11] op_sel_hi:[1,0]
	v_pk_mul_f32 v[244:245], v[244:245], s[10:11] op_sel_hi:[1,0]
	v_pk_fma_f32 v[108:109], v[108:109], 0.5, v[246:247] op_sel_hi:[1,0,1]
	v_pk_fma_f32 v[106:107], v[106:107], 0.5, v[244:245] op_sel_hi:[1,0,1]
	global_store_dwordx4 v225, v[106:109], s[84:85] offset:64
	global_load_dwordx4 v[244:247], v226, s[12:13] offset:64
	s_waitcnt vmcnt(6)
	v_pk_mul_f32 v[250:251], v[250:251], s[10:11] op_sel_hi:[1,0]
	v_pk_mul_f32 v[248:249], v[248:249], s[10:11] op_sel_hi:[1,0]
	v_pk_fma_f32 v[104:105], v[104:105], 0.5, v[250:251] op_sel_hi:[1,0,1]
	v_pk_fma_f32 v[102:103], v[102:103], 0.5, v[248:249] op_sel_hi:[1,0,1]
	global_store_dwordx4 v225, v[102:105], s[84:85] offset:512
	global_load_dwordx4 v[248:251], v226, s[12:13] offset:512
	s_waitcnt vmcnt(6)
	v_pk_mul_f32 v[254:255], v[254:255], s[10:11] op_sel_hi:[1,0]
	v_pk_mul_f32 v[252:253], v[252:253], s[10:11] op_sel_hi:[1,0]
	v_pk_fma_f32 v[96:97], v[96:97], 0.5, v[254:255] op_sel_hi:[1,0,1]
	v_pk_fma_f32 v[94:95], v[94:95], 0.5, v[252:253] op_sel_hi:[1,0,1]
	global_store_dwordx4 v225, v[94:97], s[84:85] offset:576
	global_load_dwordx4 v[252:255], v226, s[12:13] offset:576
	s_waitcnt vmcnt(6)
	v_pk_mul_f32 v[242:243], v[242:243], s[10:11] op_sel_hi:[1,0]
	v_pk_mul_f32 v[240:241], v[240:241], s[10:11] op_sel_hi:[1,0]
	s_nop 1
	v_pk_fma_f32 v[96:97], v[100:101], 0.5, v[242:243] op_sel_hi:[1,0,1]
	s_nop 1
	v_pk_fma_f32 v[94:95], v[98:99], 0.5, v[240:241] op_sel_hi:[1,0,1]
	global_store_dwordx4 v226, v[94:97], s[84:85]
	global_load_dwordx4 v[240:243], v227, s[12:13]
	s_waitcnt vmcnt(6)
	v_pk_mul_f32 v[246:247], v[246:247], s[10:11] op_sel_hi:[1,0]
	v_pk_mul_f32 v[244:245], v[244:245], s[10:11] op_sel_hi:[1,0]
	v_pk_fma_f32 v[92:93], v[92:93], 0.5, v[246:247] op_sel_hi:[1,0,1]
	v_pk_fma_f32 v[90:91], v[90:91], 0.5, v[244:245] op_sel_hi:[1,0,1]
	global_store_dwordx4 v226, v[90:93], s[84:85] offset:64
	global_load_dwordx4 v[244:247], v227, s[12:13] offset:64
	s_waitcnt vmcnt(6)
	v_pk_mul_f32 v[250:251], v[250:251], s[10:11] op_sel_hi:[1,0]
	v_pk_mul_f32 v[248:249], v[248:249], s[10:11] op_sel_hi:[1,0]
	v_pk_fma_f32 v[88:89], v[88:89], 0.5, v[250:251] op_sel_hi:[1,0,1]
	v_pk_fma_f32 v[86:87], v[86:87], 0.5, v[248:249] op_sel_hi:[1,0,1]
	global_store_dwordx4 v226, v[86:89], s[84:85] offset:512
	global_load_dwordx4 v[248:251], v227, s[12:13] offset:512
	s_waitcnt vmcnt(6)
	v_pk_mul_f32 v[254:255], v[254:255], s[10:11] op_sel_hi:[1,0]
	v_pk_mul_f32 v[252:253], v[252:253], s[10:11] op_sel_hi:[1,0]
	v_pk_fma_f32 v[80:81], v[80:81], 0.5, v[254:255] op_sel_hi:[1,0,1]
	v_pk_fma_f32 v[78:79], v[78:79], 0.5, v[252:253] op_sel_hi:[1,0,1]
	global_store_dwordx4 v226, v[78:81], s[84:85] offset:576
	global_load_dwordx4 v[252:255], v227, s[12:13] offset:576
	s_waitcnt vmcnt(6)
;     __device__ __forceinline__ void operator()(const f32x4 (&acc)[2][2][4][2], const Unit& u, int wr, int wc, int fr, int fq) const {
;         const int row0 = u.pm * BM + wr * 64 + fr; const int col0 = u.pn * BM + wc * 32 + 4 * fq;
; #pragma unroll
;         for (int ai = 0; ai < 2; ++ai)
; #pragma unroll
;             for (int m = 0; m < 4; ++m) { const size_t off = (size_t)(row0 + ai * HALF + m * 16) * D + col0;
; #pragma unroll
;                 for (int bj = 0; bj < 2; ++bj)
; #pragma unroll
;                     for (int n = 0; n < 2; ++n) { const size_t o = off + bj * HALF + n * 16; const f32x4 rv = *(const f32x4*)(res + o); *(f32x4*)(out + o) = rv * alpha + acc[ai][bj][m][n] * s; } }
	v_pk_mul_f32 v[242:243], v[242:243], s[10:11] op_sel_hi:[1,0]
	v_pk_mul_f32 v[240:241], v[240:241], s[10:11] op_sel_hi:[1,0]
	s_nop 1
	v_pk_fma_f32 v[80:81], v[84:85], 0.5, v[242:243] op_sel_hi:[1,0,1]
	s_nop 1
	v_pk_fma_f32 v[78:79], v[82:83], 0.5, v[240:241] op_sel_hi:[1,0,1]
	global_store_dwordx4 v227, v[78:81], s[84:85]
	global_load_dwordx4 v[240:243], v228, s[12:13]
	s_waitcnt vmcnt(6)
	v_pk_mul_f32 v[246:247], v[246:247], s[10:11] op_sel_hi:[1,0]
	v_pk_mul_f32 v[244:245], v[244:245], s[10:11] op_sel_hi:[1,0]
	v_pk_fma_f32 v[76:77], v[76:77], 0.5, v[246:247] op_sel_hi:[1,0,1]
	v_pk_fma_f32 v[74:75], v[74:75], 0.5, v[244:245] op_sel_hi:[1,0,1]
	global_store_dwordx4 v227, v[74:77], s[84:85] offset:64
	global_load_dwordx4 v[244:247], v228, s[12:13] offset:64
	s_waitcnt vmcnt(6)
	v_pk_mul_f32 v[250:251], v[250:251], s[10:11] op_sel_hi:[1,0]
	v_pk_mul_f32 v[248:249], v[248:249], s[10:11] op_sel_hi:[1,0]
	v_pk_fma_f32 v[72:73], v[72:73], 0.5, v[250:251] op_sel_hi:[1,0,1]
	v_pk_fma_f32 v[70:71], v[70:71], 0.5, v[248:249] op_sel_hi:[1,0,1]
	global_store_dwordx4 v227, v[70:73], s[84:85] offset:512
	global_load_dwordx4 v[248:251], v228, s[12:13] offset:512
	s_waitcnt vmcnt(6)
	v_pk_mul_f32 v[254:255], v[254:255], s[10:11] op_sel_hi:[1,0]
	v_pk_mul_f32 v[252:253], v[252:253], s[10:11] op_sel_hi:[1,0]
	v_pk_fma_f32 v[68:69], v[68:69], 0.5, v[254:255] op_sel_hi:[1,0,1]
	v_pk_fma_f32 v[66:67], v[66:67], 0.5, v[252:253] op_sel_hi:[1,0,1]
	global_store_dwordx4 v227, v[66:69], s[84:85] offset:576
	global_load_dwordx4 v[252:255], v228, s[12:13] offset:576
	s_waitcnt vmcnt(6)
	v_pk_mul_f32 v[242:243], v[242:243], s[10:11] op_sel_hi:[1,0]
	v_pk_mul_f32 v[240:241], v[240:241], s[10:11] op_sel_hi:[1,0]
	v_pk_fma_f32 v[64:65], v[64:65], 0.5, v[242:243] op_sel_hi:[1,0,1]
	v_pk_fma_f32 v[62:63], v[62:63], 0.5, v[240:241] op_sel_hi:[1,0,1]
	global_store_dwordx4 v228, v[62:65], s[84:85]
	global_load_dwordx4 v[240:243], v229, s[12:13]
	s_waitcnt vmcnt(6)
	v_pk_mul_f32 v[246:247], v[246:247], s[10:11] op_sel_hi:[1,0]
	v_pk_mul_f32 v[244:245], v[244:245], s[10:11] op_sel_hi:[1,0]
	v_pk_fma_f32 v[60:61], v[60:61], 0.5, v[246:247] op_sel_hi:[1,0,1]
	v_pk_fma_f32 v[58:59], v[58:59], 0.5, v[244:245] op_sel_hi:[1,0,1]
	global_store_dwordx4 v228, v[58:61], s[84:85] offset:64
	global_load_dwordx4 v[244:247], v229, s[12:13] offset:64
	s_waitcnt vmcnt(6)
	v_pk_mul_f32 v[250:251], v[250:251], s[10:11] op_sel_hi:[1,0]
	v_pk_mul_f32 v[248:249], v[248:249], s[10:11] op_sel_hi:[1,0]
	v_pk_fma_f32 v[56:57], v[56:57], 0.5, v[250:251] op_sel_hi:[1,0,1]
	v_pk_fma_f32 v[54:55], v[54:55], 0.5, v[248:249] op_sel_hi:[1,0,1]
	global_store_dwordx4 v228, v[54:57], s[84:85] offset:512
	global_load_dwordx4 v[248:251], v229, s[12:13] offset:512
	s_waitcnt vmcnt(6)
	v_pk_mul_f32 v[254:255], v[254:255], s[10:11] op_sel_hi:[1,0]
	v_pk_mul_f32 v[252:253], v[252:253], s[10:11] op_sel_hi:[1,0]
	v_pk_fma_f32 v[48:49], v[48:49], 0.5, v[254:255] op_sel_hi:[1,0,1]
	v_pk_fma_f32 v[46:47], v[46:47], 0.5, v[252:253] op_sel_hi:[1,0,1]
	global_store_dwordx4 v228, v[46:49], s[84:85] offset:576
	global_load_dwordx4 v[252:255], v229, s[12:13] offset:576
	s_waitcnt vmcnt(6)
	v_pk_mul_f32 v[242:243], v[242:243], s[10:11] op_sel_hi:[1,0]
	v_pk_mul_f32 v[240:241], v[240:241], s[10:11] op_sel_hi:[1,0]
	s_nop 1
	v_pk_fma_f32 v[48:49], v[52:53], 0.5, v[242:243] op_sel_hi:[1,0,1]
	s_nop 1
	v_pk_fma_f32 v[46:47], v[50:51], 0.5, v[240:241] op_sel_hi:[1,0,1]
	global_store_dwordx4 v229, v[46:49], s[84:85]
	global_load_dwordx4 v[240:243], v230, s[12:13]
	s_waitcnt vmcnt(6)
	v_pk_mul_f32 v[246:247], v[246:247], s[10:11] op_sel_hi:[1,0]
	v_pk_mul_f32 v[244:245], v[244:245], s[10:11] op_sel_hi:[1,0]
	v_pk_fma_f32 v[44:45], v[44:45], 0.5, v[246:247] op_sel_hi:[1,0,1]
	v_pk_fma_f32 v[42:43], v[42:43], 0.5, v[244:245] op_sel_hi:[1,0,1]
	global_store_dwordx4 v229, v[42:45], s[84:85] offset:64
	global_load_dwordx4 v[244:247], v230, s[12:13] offset:64
	s_waitcnt vmcnt(6)
; #define PG8_BAR __builtin_amdgcn_s_barrier()
;     __device__ __forceinline__ void operator()(const f32x4 (&acc)[2][2][4][2], const Unit& u, int wr, int wc, int fr, int fq) const {
;     ...
;             for (int m = 0; m < 4; ++m) { const size_t off = (size_t)(row0 + ai * HALF + m * 16) * D + col0;
; #pragma unroll
;                 for (int bj = 0; bj < 2; ++bj)
; #pragma unroll
;                     for (int n = 0; n < 2; ++n) { const size_t o = off + bj * HALF + n * 16; const f32x4 rv = *(const f32x4*)(res + o); *(f32x4*)(out + o) = rv * alpha + acc[ai][bj][m][n] * s; } }
; template <class Epi>
; __device__ __forceinline__ void gemm_phase(LAS unsigned char* lds, const Gemm g, const StaticOrder& S, const Epi& E) {
;     ...
;         if (wr == 0) PG8_BAR;
;         E(acc, cur, wr, wc, fr, fq);
;         if (!has_next) break;
; #pragma unroll
;         for (int a = 0; a < 2; ++a)
; #pragma unroll
;             for (int b = 0; b < 2; ++b)
; #pragma unroll
;                 for (int m = 0; m < 4; ++m)
; #pragma unroll
;                     for (int n = 0; n < 2; ++n) acc[a][b][m][n] = (f32x4){0.f, 0.f, 0.f, 0.f};
;         cur = nxt; cA = nA; cB = nB; ++ui;
;         if (wr == 1) PG8_BAR;
	v_pk_mul_f32 v[250:251], v[250:251], s[10:11] op_sel_hi:[1,0]
	v_pk_mul_f32 v[248:249], v[248:249], s[10:11] op_sel_hi:[1,0]
	v_pk_fma_f32 v[40:41], v[40:41], 0.5, v[250:251] op_sel_hi:[1,0,1]
	v_pk_fma_f32 v[38:39], v[38:39], 0.5, v[248:249] op_sel_hi:[1,0,1]
	global_store_dwordx4 v229, v[38:41], s[84:85] offset:512
	global_load_dwordx4 v[248:251], v230, s[12:13] offset:512
	s_waitcnt vmcnt(6)
	v_pk_mul_f32 v[254:255], v[254:255], s[10:11] op_sel_hi:[1,0]
	v_pk_mul_f32 v[252:253], v[252:253], s[10:11] op_sel_hi:[1,0]
	v_pk_fma_f32 v[32:33], v[32:33], 0.5, v[254:255] op_sel_hi:[1,0,1]
	v_pk_fma_f32 v[30:31], v[30:31], 0.5, v[252:253] op_sel_hi:[1,0,1]
	global_store_dwordx4 v229, v[30:33], s[84:85] offset:576
	global_load_dwordx4 v[252:255], v230, s[12:13] offset:576
	s_waitcnt vmcnt(6)
	v_pk_mul_f32 v[242:243], v[242:243], s[10:11] op_sel_hi:[1,0]
	v_pk_mul_f32 v[240:241], v[240:241], s[10:11] op_sel_hi:[1,0]
	s_nop 1
	v_pk_fma_f32 v[32:33], v[36:37], 0.5, v[242:243] op_sel_hi:[1,0,1]
	s_nop 1
	v_pk_fma_f32 v[30:31], v[34:35], 0.5, v[240:241] op_sel_hi:[1,0,1]
	global_store_dwordx4 v230, v[30:33], s[84:85]
	global_load_dwordx4 v[240:243], v231, s[12:13]
	s_waitcnt vmcnt(6)
	v_pk_mul_f32 v[246:247], v[246:247], s[10:11] op_sel_hi:[1,0]
	v_pk_mul_f32 v[244:245], v[244:245], s[10:11] op_sel_hi:[1,0]
	v_pk_fma_f32 v[28:29], v[28:29], 0.5, v[246:247] op_sel_hi:[1,0,1]
	v_pk_fma_f32 v[26:27], v[26:27], 0.5, v[244:245] op_sel_hi:[1,0,1]
	global_store_dwordx4 v230, v[26:29], s[84:85] offset:64
	global_load_dwordx4 v[244:247], v231, s[12:13] offset:64
	s_waitcnt vmcnt(6)
	v_pk_mul_f32 v[250:251], v[250:251], s[10:11] op_sel_hi:[1,0]
	v_pk_mul_f32 v[248:249], v[248:249], s[10:11] op_sel_hi:[1,0]
	v_pk_fma_f32 v[24:25], v[24:25], 0.5, v[250:251] op_sel_hi:[1,0,1]
	v_pk_fma_f32 v[22:23], v[22:23], 0.5, v[248:249] op_sel_hi:[1,0,1]
	global_store_dwordx4 v230, v[22:25], s[84:85] offset:512
	global_load_dwordx4 v[248:251], v231, s[12:13] offset:512
	s_waitcnt vmcnt(6)
	v_pk_mul_f32 v[254:255], v[254:255], s[10:11] op_sel_hi:[1,0]
	v_pk_mul_f32 v[252:253], v[252:253], s[10:11] op_sel_hi:[1,0]
	v_pk_fma_f32 v[16:17], v[16:17], 0.5, v[254:255] op_sel_hi:[1,0,1]
	v_pk_fma_f32 v[14:15], v[14:15], 0.5, v[252:253] op_sel_hi:[1,0,1]
	global_store_dwordx4 v230, v[14:17], s[84:85] offset:576
	global_load_dwordx4 v[252:255], v231, s[12:13] offset:576
	s_waitcnt vmcnt(6)
	v_pk_mul_f32 v[242:243], v[242:243], s[10:11] op_sel_hi:[1,0]
	v_pk_mul_f32 v[240:241], v[240:241], s[10:11] op_sel_hi:[1,0]
	s_nop 1
	v_pk_fma_f32 v[16:17], v[20:21], 0.5, v[242:243] op_sel_hi:[1,0,1]
	s_nop 1
	v_pk_fma_f32 v[14:15], v[18:19], 0.5, v[240:241] op_sel_hi:[1,0,1]
	global_store_dwordx4 v231, v[14:17], s[84:85]
	s_waitcnt vmcnt(5)
	v_pk_mul_f32 v[246:247], v[246:247], s[10:11] op_sel_hi:[1,0]
	v_pk_mul_f32 v[244:245], v[244:245], s[10:11] op_sel_hi:[1,0]
	v_pk_fma_f32 v[12:13], v[12:13], 0.5, v[246:247] op_sel_hi:[1,0,1]
	v_pk_fma_f32 v[10:11], v[10:11], 0.5, v[244:245] op_sel_hi:[1,0,1]
	global_store_dwordx4 v231, v[10:13], s[84:85] offset:64
	s_waitcnt vmcnt(4)
	v_pk_mul_f32 v[250:251], v[250:251], s[10:11] op_sel_hi:[1,0]
	v_pk_mul_f32 v[248:249], v[248:249], s[10:11] op_sel_hi:[1,0]
	v_pk_fma_f32 v[8:9], v[8:9], 0.5, v[250:251] op_sel_hi:[1,0,1]
	v_pk_fma_f32 v[6:7], v[6:7], 0.5, v[248:249] op_sel_hi:[1,0,1]
	global_store_dwordx4 v231, v[6:9], s[84:85] offset:512
	s_waitcnt vmcnt(3)
	v_pk_mul_f32 v[254:255], v[254:255], s[10:11] op_sel_hi:[1,0]
	v_pk_mul_f32 v[252:253], v[252:253], s[10:11] op_sel_hi:[1,0]
	v_pk_fma_f32 v[4:5], v[4:5], 0.5, v[254:255] op_sel_hi:[1,0,1]
	v_pk_fma_f32 v[2:3], v[2:3], 0.5, v[252:253] op_sel_hi:[1,0,1]
	global_store_dwordx4 v231, v[2:5], s[84:85] offset:576
	s_cbranch_vccnz .LBB0_152
	s_andn2_b64 vcc, exec, s[2:3]
	s_cbranch_vccnz .LBB0_151
	s_barrier
	s_branch .LBB0_151
